# combo15 + memory cross-attention block: the 8 K-fragment ds_read_b128 of each QK chain issued together ahead of the MFMAs (MFMA/LDS interleave on xatt)
# speedup vs baseline: 1.0093x; 1.0058x over previous
.LBB0_303:
	v_lshl_add_u32 v64, v130, 1, s21
	v_add_u32_e32 v161, v64, v153
	ds_read_b128 v[64:67], v161
	ds_read_b128 v[192:195], v161 offset:32
	ds_read_b128 v[196:199], v161 offset:64
	ds_read_b128 v[200:203], v161 offset:96
	ds_read_b128 v[220:223], v161 offset:128
	ds_read_b128 v[224:227], v161 offset:160
	ds_read_b128 v[228:231], v161 offset:192
	ds_read_b128 v[232:235], v161 offset:224
	s_waitcnt lgkmcnt(0)
	v_mfma_f32_32x32x16_bf16 v[64:79], v[64:67], v[80:83], 0
	v_mfma_f32_32x32x16_bf16 v[64:79], v[192:195], v[84:87], v[64:79]
	v_mfma_f32_32x32x16_bf16 v[64:79], v[196:199], v[88:91], v[64:79]
	v_mfma_f32_32x32x16_bf16 v[64:79], v[200:203], v[92:95], v[64:79]
	v_mfma_f32_32x32x16_bf16 v[64:79], v[220:223], v[96:99], v[64:79]
	v_mfma_f32_32x32x16_bf16 v[64:79], v[224:227], v[100:103], v[64:79]
	v_mfma_f32_32x32x16_bf16 v[64:79], v[228:231], v[104:107], v[64:79]
	v_mfma_f32_32x32x16_bf16 v[64:79], v[232:235], v[108:111], v[64:79]
	s_nop 11
	v_mul_f32_e32 v160, 0x3e0293ee, v64
	v_mul_f32_e32 v162, 0x3e0293ee, v65
	v_mul_f32_e32 v65, 0x3e0293ee, v78
	v_mul_f32_e32 v64, 0x3e0293ee, v79
	v_mul_f32_e32 v163, 0x3e0293ee, v66
	v_mul_f32_e32 v164, 0x3e0293ee, v67
	v_mul_f32_e32 v158, 0x3e0293ee, v68
	v_mul_f32_e32 v157, 0x3e0293ee, v69
	v_mul_f32_e32 v156, 0x3e0293ee, v70
	v_mul_f32_e32 v155, 0x3e0293ee, v71
	v_mul_f32_e32 v71, 0x3e0293ee, v72
	v_mul_f32_e32 v70, 0x3e0293ee, v73
	v_mul_f32_e32 v69, 0x3e0293ee, v74
	v_mul_f32_e32 v68, 0x3e0293ee, v75
	v_mul_f32_e32 v67, 0x3e0293ee, v76
	v_mul_f32_e32 v66, 0x3e0293ee, v77
	v_max_f32_e32 v76, v65, v64
	v_max_f32_e32 v72, v163, v164
	v_max_f32_e32 v73, v156, v155
	v_max_f32_e32 v74, v71, v70
	v_max_f32_e32 v75, v69, v68
	v_max3_f32 v76, v67, v66, v76
	v_max3_f32 v72, v160, v162, v72
	v_max3_f32 v73, v158, v157, v73
	v_max3_f32 v74, v74, v75, v76
	v_max3_f32 v72, v72, v73, v74
	ds_bpermute_b32 v73, v150, v72
	s_waitcnt lgkmcnt(0)
	v_max3_f32 v159, v154, v72, v73
	v_cmp_neq_f32_e32 vcc, s29, v159
	s_nop 1
	v_cndmask_b32_e32 v72, 0, v159, vcc
	v_sub_f32_e32 v73, v154, v72
	v_exp_f32_e32 v148, v73
	s_nop 0
	v_cmp_eq_f32_e32 vcc, 1.0, v148
	s_cmp_eq_u64 vcc, exec
	s_cbranch_scc1 .LBB0_305
	v_pk_mul_f32 v[62:63], v[62:63], v[148:149] op_sel_hi:[1,0]
	v_pk_mul_f32 v[60:61], v[60:61], v[148:149] op_sel_hi:[1,0]
	v_pk_mul_f32 v[58:59], v[58:59], v[148:149] op_sel_hi:[1,0]
	v_pk_mul_f32 v[56:57], v[56:57], v[148:149] op_sel_hi:[1,0]
	v_pk_mul_f32 v[54:55], v[54:55], v[148:149] op_sel_hi:[1,0]
	v_pk_mul_f32 v[52:53], v[52:53], v[148:149] op_sel_hi:[1,0]
	v_pk_mul_f32 v[50:51], v[50:51], v[148:149] op_sel_hi:[1,0]
	v_pk_mul_f32 v[48:49], v[48:49], v[148:149] op_sel_hi:[1,0]
	v_pk_mul_f32 v[46:47], v[46:47], v[148:149] op_sel_hi:[1,0]
	v_pk_mul_f32 v[44:45], v[44:45], v[148:149] op_sel_hi:[1,0]
	v_pk_mul_f32 v[42:43], v[42:43], v[148:149] op_sel_hi:[1,0]
	v_pk_mul_f32 v[40:41], v[40:41], v[148:149] op_sel_hi:[1,0]
	v_pk_mul_f32 v[38:39], v[38:39], v[148:149] op_sel_hi:[1,0]
	v_pk_mul_f32 v[36:37], v[36:37], v[148:149] op_sel_hi:[1,0]
	v_pk_mul_f32 v[34:35], v[34:35], v[148:149] op_sel_hi:[1,0]
	v_pk_mul_f32 v[32:33], v[32:33], v[148:149] op_sel_hi:[1,0]
	v_pk_mul_f32 v[30:31], v[30:31], v[148:149] op_sel_hi:[1,0]
	v_pk_mul_f32 v[28:29], v[28:29], v[148:149] op_sel_hi:[1,0]
	v_pk_mul_f32 v[26:27], v[26:27], v[148:149] op_sel_hi:[1,0]
	v_pk_mul_f32 v[24:25], v[24:25], v[148:149] op_sel_hi:[1,0]
	v_pk_mul_f32 v[22:23], v[22:23], v[148:149] op_sel_hi:[1,0]
	v_pk_mul_f32 v[20:21], v[20:21], v[148:149] op_sel_hi:[1,0]
	v_pk_mul_f32 v[18:19], v[18:19], v[148:149] op_sel_hi:[1,0]
	v_pk_mul_f32 v[16:17], v[16:17], v[148:149] op_sel_hi:[1,0]
	v_pk_mul_f32 v[14:15], v[14:15], v[148:149] op_sel_hi:[1,0]
	v_pk_mul_f32 v[12:13], v[12:13], v[148:149] op_sel_hi:[1,0]
	v_pk_mul_f32 v[10:11], v[10:11], v[148:149] op_sel_hi:[1,0]
	v_pk_mul_f32 v[8:9], v[8:9], v[148:149] op_sel_hi:[1,0]
	v_pk_mul_f32 v[6:7], v[6:7], v[148:149] op_sel_hi:[1,0]
	v_pk_mul_f32 v[4:5], v[4:5], v[148:149] op_sel_hi:[1,0]
	v_pk_mul_f32 v[2:3], v[2:3], v[148:149] op_sel_hi:[1,0]
	v_pk_mul_f32 v[0:1], v[0:1], v[148:149] op_sel_hi:[1,0]
.LBB0_305:
	v_sub_f32_e32 v74, v160, v72
	v_exp_f32_e32 v160, v74
	v_sub_f32_e32 v74, v162, v72
	v_exp_f32_e32 v162, v74
	v_sub_f32_e32 v74, v163, v72
	v_exp_f32_e32 v163, v74
	v_sub_f32_e32 v74, v164, v72
	v_exp_f32_e32 v164, v74
	v_sub_f32_e32 v74, v158, v72
	v_exp_f32_e32 v165, v74
	v_sub_f32_e32 v74, v157, v72
	v_add_u32_e32 v73, s21, v130
	v_exp_f32_e32 v166, v74
	v_sub_f32_e32 v74, v156, v72
	v_exp_f32_e32 v167, v74
	v_sub_f32_e32 v74, v155, v72
	v_add_u32_e32 v154, v73, v152
	v_exp_f32_e32 v168, v74
	v_add_u32_e32 v157, 0x4000, v154
	v_sub_f32_e32 v71, v71, v72
	v_sub_f32_e32 v70, v70, v72
	v_sub_f32_e32 v69, v69, v72
	v_sub_f32_e32 v68, v68, v72
	v_sub_f32_e32 v67, v67, v72
	v_sub_f32_e32 v66, v66, v72
	v_sub_f32_e32 v65, v65, v72
	v_sub_f32_e32 v64, v64, v72
	ds_read2_b64 v[72:75], v157 offset0:128 offset1:130
	ds_read2_b64 v[76:79], v157 offset0:132 offset1:134
	v_exp_f32_e32 v174, v67
	v_exp_f32_e32 v175, v66
	v_exp_f32_e32 v180, v65
	v_exp_f32_e32 v181, v64
	v_cvt_pk_bf16_f32 v64, v160, v162
	v_cvt_pk_bf16_f32 v65, v163, v164
	v_cvt_pk_bf16_f32 v66, v165, v166
	v_cvt_pk_bf16_f32 v67, v167, v168
	v_exp_f32_e32 v169, v71
	v_exp_f32_e32 v171, v70
	s_waitcnt lgkmcnt(0)
	v_mfma_f32_32x32x16_bf16 v[48:63], v[72:75], v[64:67], v[48:63]
	v_exp_f32_e32 v172, v69
	v_exp_f32_e32 v173, v68
	v_cvt_pk_bf16_f32 v68, v169, v171
	v_cvt_pk_bf16_f32 v70, v174, v175
	v_cvt_pk_bf16_f32 v71, v180, v181
	v_cvt_pk_bf16_f32 v69, v172, v173
	v_add_u32_e32 v158, 0x5000, v154
	v_add_u32_e32 v156, 0x6000, v154
	v_mfma_f32_32x32x16_bf16 v[48:63], v[76:79], v[68:71], v[48:63]
	ds_read2_b64 v[72:75], v158 offset0:160 offset1:162
	ds_read2_b64 v[76:79], v158 offset0:164 offset1:166
	v_add_u32_e32 v155, 0x7000, v154
	s_waitcnt lgkmcnt(0)
	v_mfma_f32_32x32x16_bf16 v[32:47], v[72:75], v[64:67], v[32:47]
	v_mfma_f32_32x32x16_bf16 v[32:47], v[76:79], v[68:71], v[32:47]
	ds_read2_b64 v[72:75], v156 offset0:192 offset1:194
	ds_read2_b64 v[76:79], v156 offset0:196 offset1:198
	s_waitcnt lgkmcnt(0)
	v_mfma_f32_32x32x16_bf16 v[16:31], v[72:75], v[64:67], v[16:31]
	v_mfma_f32_32x32x16_bf16 v[16:31], v[76:79], v[68:71], v[16:31]
	ds_read2_b64 v[72:75], v155 offset0:224 offset1:226
	ds_read2_b64 v[76:79], v155 offset0:228 offset1:230
	s_waitcnt lgkmcnt(0)
	v_mfma_f32_32x32x16_bf16 v[0:15], v[72:75], v[64:67], v[0:15]
	v_mfma_f32_32x32x16_bf16 v[0:15], v[76:79], v[68:71], v[0:15]
	ds_read_b128 v[64:67], v161 offset:8704
	ds_read_b128 v[192:195], v161 offset:8736
	ds_read_b128 v[196:199], v161 offset:8768
	ds_read_b128 v[200:203], v161 offset:8800
	ds_read_b128 v[220:223], v161 offset:8832
	ds_read_b128 v[224:227], v161 offset:8864
	ds_read_b128 v[228:231], v161 offset:8896
	ds_read_b128 v[232:235], v161 offset:8928
	s_waitcnt lgkmcnt(0)
	v_mfma_f32_32x32x16_bf16 v[64:79], v[64:67], v[80:83], 0
	v_mfma_f32_32x32x16_bf16 v[64:79], v[192:195], v[84:87], v[64:79]
	v_mfma_f32_32x32x16_bf16 v[64:79], v[196:199], v[88:91], v[64:79]
	v_mfma_f32_32x32x16_bf16 v[64:79], v[200:203], v[92:95], v[64:79]
	v_mfma_f32_32x32x16_bf16 v[64:79], v[220:223], v[96:99], v[64:79]
	v_mfma_f32_32x32x16_bf16 v[64:79], v[224:227], v[100:103], v[64:79]
	v_mfma_f32_32x32x16_bf16 v[64:79], v[228:231], v[104:107], v[64:79]
	v_mfma_f32_32x32x16_bf16 v[64:79], v[232:235], v[108:111], v[64:79]
	s_nop 11
	v_mul_f32_e32 v187, 0x3e0293ee, v65
	v_mul_f32_e32 v185, 0x3e0293ee, v67
	v_mul_f32_e32 v67, 0x3e0293ee, v78
	v_mul_f32_e32 v65, 0x3e0293ee, v79
	v_mul_f32_e32 v186, 0x3e0293ee, v66
	v_mul_f32_e32 v184, 0x3e0293ee, v68
	v_mul_f32_e32 v183, 0x3e0293ee, v69
	v_mul_f32_e32 v182, 0x3e0293ee, v70
	v_mul_f32_e32 v161, 0x3e0293ee, v71
	v_mul_f32_e32 v72, 0x3e0293ee, v72
	v_mul_f32_e32 v71, 0x3e0293ee, v73
	v_mul_f32_e32 v70, 0x3e0293ee, v74
	v_mul_f32_e32 v69, 0x3e0293ee, v75
	v_mul_f32_e32 v66, 0x3e0293ee, v76
	v_mul_f32_e32 v68, 0x3e0293ee, v77
	v_max_f32_e32 v76, v67, v65
	v_mul_f32_e32 v188, 0x3e0293ee, v64
	v_max_f32_e32 v64, v186, v185
	v_max_f32_e32 v73, v182, v161
	v_max_f32_e32 v74, v72, v71
	v_max_f32_e32 v75, v70, v69
	v_max3_f32 v76, v66, v68, v76
	v_max3_f32 v64, v188, v187, v64
	v_max3_f32 v73, v184, v183, v73
	v_max3_f32 v74, v74, v75, v76
	v_max3_f32 v64, v64, v73, v74
	ds_bpermute_b32 v73, v150, v64
	s_waitcnt lgkmcnt(0)
	v_max3_f32 v154, v159, v64, v73
	v_cmp_neq_f32_e32 vcc, s29, v154
	s_nop 1
	v_cndmask_b32_e32 v73, 0, v154, vcc
	v_sub_f32_e32 v64, v159, v73
	v_exp_f32_e32 v64, v64
	s_nop 0
	v_cmp_eq_f32_e32 vcc, 1.0, v64
	s_cmp_eq_u64 vcc, exec
	s_cbranch_scc1 .LBB0_300
	v_pk_mul_f32 v[62:63], v[62:63], v[64:65] op_sel_hi:[1,0]
	v_pk_mul_f32 v[60:61], v[60:61], v[64:65] op_sel_hi:[1,0]
	v_pk_mul_f32 v[58:59], v[58:59], v[64:65] op_sel_hi:[1,0]
	v_pk_mul_f32 v[56:57], v[56:57], v[64:65] op_sel_hi:[1,0]
	v_pk_mul_f32 v[54:55], v[54:55], v[64:65] op_sel_hi:[1,0]
	v_pk_mul_f32 v[52:53], v[52:53], v[64:65] op_sel_hi:[1,0]
	v_pk_mul_f32 v[50:51], v[50:51], v[64:65] op_sel_hi:[1,0]
	v_pk_mul_f32 v[48:49], v[48:49], v[64:65] op_sel_hi:[1,0]
	v_pk_mul_f32 v[46:47], v[46:47], v[64:65] op_sel_hi:[1,0]
	v_pk_mul_f32 v[44:45], v[44:45], v[64:65] op_sel_hi:[1,0]
	v_pk_mul_f32 v[42:43], v[42:43], v[64:65] op_sel_hi:[1,0]
	v_pk_mul_f32 v[40:41], v[40:41], v[64:65] op_sel_hi:[1,0]
	v_pk_mul_f32 v[38:39], v[38:39], v[64:65] op_sel_hi:[1,0]
	v_pk_mul_f32 v[36:37], v[36:37], v[64:65] op_sel_hi:[1,0]
	v_pk_mul_f32 v[34:35], v[34:35], v[64:65] op_sel_hi:[1,0]
	v_pk_mul_f32 v[32:33], v[32:33], v[64:65] op_sel_hi:[1,0]
	v_pk_mul_f32 v[30:31], v[30:31], v[64:65] op_sel_hi:[1,0]
	v_pk_mul_f32 v[28:29], v[28:29], v[64:65] op_sel_hi:[1,0]
	v_pk_mul_f32 v[26:27], v[26:27], v[64:65] op_sel_hi:[1,0]
	v_pk_mul_f32 v[24:25], v[24:25], v[64:65] op_sel_hi:[1,0]
	v_pk_mul_f32 v[22:23], v[22:23], v[64:65] op_sel_hi:[1,0]
	v_pk_mul_f32 v[20:21], v[20:21], v[64:65] op_sel_hi:[1,0]
	v_pk_mul_f32 v[18:19], v[18:19], v[64:65] op_sel_hi:[1,0]
	v_pk_mul_f32 v[16:17], v[16:17], v[64:65] op_sel_hi:[1,0]
	v_pk_mul_f32 v[14:15], v[14:15], v[64:65] op_sel_hi:[1,0]
	v_pk_mul_f32 v[12:13], v[12:13], v[64:65] op_sel_hi:[1,0]
	v_pk_mul_f32 v[10:11], v[10:11], v[64:65] op_sel_hi:[1,0]
	v_pk_mul_f32 v[8:9], v[8:9], v[64:65] op_sel_hi:[1,0]
	v_pk_mul_f32 v[6:7], v[6:7], v[64:65] op_sel_hi:[1,0]
	v_pk_mul_f32 v[4:5], v[4:5], v[64:65] op_sel_hi:[1,0]
	v_pk_mul_f32 v[2:3], v[2:3], v[64:65] op_sel_hi:[1,0]
	v_pk_mul_f32 v[0:1], v[0:1], v[64:65] op_sel_hi:[1,0]
	s_branch .LBB0_300
